# latent attention tile loops software-pipelined: K fragments prefetched a tile ahead, V fragments read under the QK MFMAs
# speedup vs baseline: 1.0181x; 1.0081x over previous
.LBB0_376:
	v_readlane_b32 s6, v255, 21
	v_readlane_b32 s7, v255, 22
	v_cmp_eq_u32_e64 s[0:1], 0, v5
	s_andn2_b64 vcc, exec, s[6:7]
	s_movk_i32 s2, 0x288
	s_movk_i32 s6, 0x90
	v_lshlrev_b32_e32 v119, 2, v5
	s_waitcnt vmcnt(0)
	v_mul_f32_e32 v183, 0x3fb8aa3b, v1
	v_cndmask_b32_e64 v182, 0, 1.0, s[0:1]
	v_mad_u32_u24 v123, v2, s2, v198
	v_mad_u32_u24 v127, v2, s6, v0
	s_waitcnt lgkmcnt(0)
	s_barrier
	s_cbranch_vccnz .LBB0_386
	v_mbcnt_hi_u32_b32 v1, -1, v197
	v_readfirstlane_b32 s32, v4
	v_and_b32_e32 v5, 64, v1
	v_mad_u32_u24 v173, v2, s6, v0
	v_readlane_b32 s6, v255, 25
	v_add_u32_e32 v129, 0xffffff9f, v4
	v_add_u32_e32 v151, 0x41, v4
	v_xor_b32_e32 v4, 32, v1
	v_add_u32_e32 v5, 64, v5
	v_add3_u32 v0, s6, v3, v2
	v_readlane_b32 s6, v255, 28
	v_cmp_lt_i32_e32 vcc, v4, v5
	v_sub_u32_e32 v179, v0, v119
	v_add_u32_e32 v0, s6, v119
	v_cndmask_b32_e32 v1, v1, v4, vcc
	v_sub_u32_e32 v0, v0, v2
	v_mov_b32_e32 v16, 0
	v_lshlrev_b32_e32 v155, 2, v1
	s_movk_i32 s2, 0x90
	v_sub_u32_e32 v180, v0, v3
	v_readlane_b32 s19, v255, 26
	v_mov_b32_e32 v181, v123
	v_readlane_b32 s21, v255, 20
	v_mov_b32_e32 v17, v16
	v_mov_b32_e32 v18, v16
	v_mov_b32_e32 v19, v16
	v_mov_b32_e32 v20, v16
	v_mov_b32_e32 v21, v16
	v_mov_b32_e32 v22, v16
	v_mov_b32_e32 v23, v16
	v_mov_b32_e32 v24, v16
	v_mov_b32_e32 v25, v16
	v_mov_b32_e32 v26, v16
	v_mov_b32_e32 v27, v16
	v_mov_b32_e32 v28, v16
	v_mov_b32_e32 v29, v16
	v_mov_b32_e32 v30, v16
	v_mov_b32_e32 v31, v16
	v_mov_b32_e32 v0, v16
	v_mov_b32_e32 v1, v16
	v_mov_b32_e32 v2, v16
	v_mov_b32_e32 v3, v16
	v_mov_b32_e32 v4, v16
	v_mov_b32_e32 v5, v16
	v_mov_b32_e32 v6, v16
	v_mov_b32_e32 v7, v16
	v_mov_b32_e32 v8, v16
	v_mov_b32_e32 v9, v16
	v_mov_b32_e32 v10, v16
	v_mov_b32_e32 v11, v16
	v_mov_b32_e32 v12, v16
	v_mov_b32_e32 v13, v16
	v_mov_b32_e32 v14, v16
	v_mov_b32_e32 v15, v16
	v_add_u32_e32 v234, 0xb400, v123
	v_add_u32_e32 v235, 0x10500, v123
	ds_read_b128 v[202:205], v173
	ds_read_b128 v[206:209], v173 offset:32
	ds_read_b128 v[210:213], v173 offset:64
	ds_read_b128 v[214:217], v173 offset:96
	ds_read_b128 v[218:221], v173 offset:4608
	ds_read_b128 v[222:225], v173 offset:4640
	ds_read_b128 v[226:229], v173 offset:4672
	ds_read_b128 v[230:233], v173 offset:4704
	v_add_u32_e32 v173, 0x2400, v173
.Llat1_top:
	s_waitcnt lgkmcnt(7)
	v_mfma_f32_32x32x16_bf16 v[48:63], v[202:205], v[96:99], 0
	ds_read2_b64 v[202:205], v234 offset1:2
	s_waitcnt lgkmcnt(7)
	v_mfma_f32_32x32x16_bf16 v[48:63], v[206:209], v[100:103], v[48:63]
	ds_read2_b64 v[206:209], v234 offset0:4 offset1:6
	s_waitcnt lgkmcnt(7)
	v_mfma_f32_32x32x16_bf16 v[48:63], v[210:213], v[104:107], v[48:63]
	ds_read2_b64 v[210:213], v235 offset1:2
	s_waitcnt lgkmcnt(7)
	v_mfma_f32_32x32x16_bf16 v[48:63], v[214:217], v[108:111], v[48:63]
	ds_read2_b64 v[214:217], v235 offset0:4 offset1:6
	s_waitcnt lgkmcnt(7)
	v_mfma_f32_32x32x16_bf16 v[32:47], v[218:221], v[96:99], 0
	ds_read2_b64 v[218:221], v234 offset0:8 offset1:10
	s_waitcnt lgkmcnt(7)
	v_mfma_f32_32x32x16_bf16 v[32:47], v[222:225], v[100:103], v[32:47]
	ds_read2_b64 v[222:225], v234 offset0:12 offset1:14
	s_waitcnt lgkmcnt(7)
	v_mfma_f32_32x32x16_bf16 v[32:47], v[226:229], v[104:107], v[32:47]
	ds_read2_b64 v[226:229], v235 offset0:8 offset1:10
	s_waitcnt lgkmcnt(7)
	v_mfma_f32_32x32x16_bf16 v[32:47], v[230:233], v[108:111], v[32:47]
	ds_read2_b64 v[230:233], v235 offset0:12 offset1:14
	s_cmp_lg_u64 s[4:5], 0
	s_cbranch_scc1 .Llat1_plainmax
	s_sub_i32 s63, s19, s32
	s_add_i32 s63, s63, 0x61
	s_cmp_lt_u32 s63, 0xa3
	s_cbranch_scc1 .Llat1_plainmax
	v_add_u32_e32 v236, 59, v179
	v_cmp_lt_u32_e32 vcc, s17, v236
	v_add_u32_e32 v237, 57, v179
	s_nop 0
	v_cndmask_b32_e32 v48, v252, v48, vcc
	v_cmp_gt_u32_e32 vcc, s31, v180
	s_nop 1
	v_cndmask_b32_e32 v49, v252, v49, vcc
	v_cmp_lt_u32_e32 vcc, s17, v237
	v_add_u32_e32 v237, 56, v179
	v_max3_f32 v236, v48, s16, v49
	v_cndmask_b32_e32 v50, v252, v50, vcc
	v_cmp_lt_u32_e32 vcc, s17, v237
	v_add_u32_e32 v237, 51, v179
	s_nop 0
	v_cndmask_b32_e32 v51, v252, v51, vcc
	v_cmp_lt_u32_e32 vcc, s17, v237
	v_add_u32_e32 v237, 50, v179
	v_max3_f32 v236, v236, v50, v51
	v_cndmask_b32_e32 v52, v252, v52, vcc
	v_cmp_lt_u32_e32 vcc, s17, v237
	v_add_u32_e32 v237, 49, v179
	s_nop 0
	v_cndmask_b32_e32 v53, v252, v53, vcc
	v_cmp_lt_u32_e32 vcc, s17, v237
	v_add_u32_e32 v237, 48, v179
	v_max3_f32 v236, v236, v52, v53
	v_cndmask_b32_e32 v54, v252, v54, vcc
	v_cmp_lt_u32_e32 vcc, s17, v237
	v_add_u32_e32 v237, 43, v179
	s_nop 0
	v_cndmask_b32_e32 v55, v252, v55, vcc
	v_cmp_lt_u32_e32 vcc, s17, v237
	v_add_u32_e32 v237, 42, v179
	v_max3_f32 v236, v236, v54, v55
	v_cndmask_b32_e32 v56, v252, v56, vcc
	v_cmp_lt_u32_e32 vcc, s17, v237
	v_add_u32_e32 v237, 41, v179
	s_nop 0
	v_cndmask_b32_e32 v57, v252, v57, vcc
	v_cmp_lt_u32_e32 vcc, s17, v237
	v_add_u32_e32 v237, 40, v179
	v_max3_f32 v236, v236, v56, v57
	v_cndmask_b32_e32 v58, v252, v58, vcc
	v_cmp_lt_u32_e32 vcc, s17, v237
	v_add_u32_e32 v237, 35, v179
	s_nop 0
	v_cndmask_b32_e32 v59, v252, v59, vcc
	v_cmp_lt_u32_e32 vcc, s17, v237
	v_add_u32_e32 v237, 34, v179
	v_max3_f32 v236, v236, v58, v59
	v_cndmask_b32_e32 v60, v252, v60, vcc
	v_cmp_lt_u32_e32 vcc, s17, v237
	v_add_u32_e32 v237, 33, v179
	s_nop 0
	v_cndmask_b32_e32 v61, v252, v61, vcc
	v_cmp_lt_u32_e32 vcc, s17, v237
	v_add_u32_e32 v237, 32, v179
	v_max3_f32 v236, v236, v60, v61
	v_cndmask_b32_e32 v62, v252, v62, vcc
	v_cmp_lt_u32_e32 vcc, s17, v237
	v_add_u32_e32 v237, 27, v179
	s_nop 0
	v_cndmask_b32_e32 v63, v252, v63, vcc
	v_cmp_lt_u32_e32 vcc, s17, v237
	v_add_u32_e32 v237, 26, v179
	v_max3_f32 v236, v236, v62, v63
	v_cndmask_b32_e32 v32, v252, v32, vcc
	v_cmp_lt_u32_e32 vcc, s17, v237
	v_add_u32_e32 v237, 25, v179
	s_nop 0
	v_cndmask_b32_e32 v33, v252, v33, vcc
	v_cmp_lt_u32_e32 vcc, s17, v237
	v_add_u32_e32 v237, 24, v179
	v_max3_f32 v236, v236, v32, v33
	v_cndmask_b32_e32 v34, v252, v34, vcc
	v_cmp_lt_u32_e32 vcc, s17, v237
	v_add_u32_e32 v237, 19, v179
	s_nop 0
	v_cndmask_b32_e32 v35, v252, v35, vcc
	v_cmp_lt_u32_e32 vcc, s17, v237
	v_add_u32_e32 v237, 18, v179
	v_max3_f32 v236, v236, v34, v35
	v_cndmask_b32_e32 v36, v252, v36, vcc
	v_cmp_lt_u32_e32 vcc, s17, v237
	v_add_u32_e32 v237, 17, v179
	s_nop 0
	v_cndmask_b32_e32 v37, v252, v37, vcc
	v_cmp_lt_u32_e32 vcc, s17, v237
	v_add_u32_e32 v237, 16, v179
	v_max3_f32 v236, v236, v36, v37
	v_cndmask_b32_e32 v38, v252, v38, vcc
	v_cmp_lt_u32_e32 vcc, s17, v237
	v_add_u32_e32 v237, 11, v179
	s_nop 0
	v_cndmask_b32_e32 v39, v252, v39, vcc
	v_cmp_lt_u32_e32 vcc, s17, v237
	v_add_u32_e32 v237, 10, v179
	v_max3_f32 v236, v236, v38, v39
	v_cndmask_b32_e32 v40, v252, v40, vcc
	v_cmp_lt_u32_e32 vcc, s17, v237
	v_add_u32_e32 v237, 9, v179
	s_nop 0
	v_cndmask_b32_e32 v41, v252, v41, vcc
	v_cmp_lt_u32_e32 vcc, s17, v237
	v_add_u32_e32 v237, 8, v179
	v_max3_f32 v236, v236, v40, v41
	v_cndmask_b32_e32 v42, v252, v42, vcc
	v_cmp_lt_u32_e32 vcc, s17, v237
	v_add_u32_e32 v237, 3, v179
	s_nop 0
	v_cndmask_b32_e32 v43, v252, v43, vcc
	v_cmp_lt_u32_e32 vcc, s17, v237
	v_add_u32_e32 v237, 2, v179
	v_max3_f32 v236, v236, v42, v43
	v_cndmask_b32_e32 v44, v252, v44, vcc
	v_cmp_lt_u32_e32 vcc, s17, v237
	v_add_u32_e32 v237, 1, v179
	s_nop 0
	v_cndmask_b32_e32 v45, v252, v45, vcc
	v_cmp_lt_u32_e32 vcc, s17, v237
	v_max3_f32 v236, v236, v44, v45
	s_nop 0
	v_cndmask_b32_e32 v46, v252, v46, vcc
	v_cmp_lt_u32_e32 vcc, s17, v179
	s_nop 1
	v_cndmask_b32_e32 v47, v252, v47, vcc
	v_max3_f32 v236, v236, v46, v47
	s_branch .Llat1_maxdone
.Llat1_plainmax:
	v_max3_f32 v236, v48, s16, v49
	v_max3_f32 v236, v236, v50, v51
	v_max3_f32 v236, v236, v52, v53
	v_max3_f32 v236, v236, v54, v55
	v_max3_f32 v236, v236, v56, v57
	v_max3_f32 v236, v236, v58, v59
	v_max3_f32 v236, v236, v60, v61
	v_max3_f32 v236, v236, v62, v63
	s_nop 3
	v_max3_f32 v236, v236, v32, v33
	v_max3_f32 v236, v236, v34, v35
	v_max3_f32 v236, v236, v36, v37
	v_max3_f32 v236, v236, v38, v39
	v_max3_f32 v236, v236, v40, v41
	v_max3_f32 v236, v236, v42, v43
	v_max3_f32 v236, v236, v44, v45
	v_max3_f32 v236, v236, v46, v47
.Llat1_maxdone:
	ds_bpermute_b32 v237, v155, v236
	s_waitcnt lgkmcnt(0)
	v_max3_f32 v236, v183, v236, v237
	v_sub_f32_e32 v238, v183, v236
	v_pk_add_f32 v[48:49], v[48:49], v[236:237] op_sel_hi:[1,0] neg_lo:[0,1] neg_hi:[0,1]
	v_pk_add_f32 v[50:51], v[50:51], v[236:237] op_sel_hi:[1,0] neg_lo:[0,1] neg_hi:[0,1]
	v_pk_add_f32 v[52:53], v[52:53], v[236:237] op_sel_hi:[1,0] neg_lo:[0,1] neg_hi:[0,1]
	v_pk_add_f32 v[54:55], v[54:55], v[236:237] op_sel_hi:[1,0] neg_lo:[0,1] neg_hi:[0,1]
	v_pk_add_f32 v[56:57], v[56:57], v[236:237] op_sel_hi:[1,0] neg_lo:[0,1] neg_hi:[0,1]
	v_pk_add_f32 v[58:59], v[58:59], v[236:237] op_sel_hi:[1,0] neg_lo:[0,1] neg_hi:[0,1]
	v_pk_add_f32 v[60:61], v[60:61], v[236:237] op_sel_hi:[1,0] neg_lo:[0,1] neg_hi:[0,1]
	v_pk_add_f32 v[62:63], v[62:63], v[236:237] op_sel_hi:[1,0] neg_lo:[0,1] neg_hi:[0,1]
	v_exp_f32_e32 v238, v238
	v_exp_f32_e32 v48, v48
	v_exp_f32_e32 v49, v49
	v_exp_f32_e32 v50, v50
	v_exp_f32_e32 v51, v51
	v_exp_f32_e32 v52, v52
	v_exp_f32_e32 v53, v53
	v_exp_f32_e32 v54, v54
	v_exp_f32_e32 v55, v55
	v_exp_f32_e32 v56, v56
	v_exp_f32_e32 v57, v57
	v_exp_f32_e32 v58, v58
	v_exp_f32_e32 v59, v59
	v_exp_f32_e32 v60, v60
	v_exp_f32_e32 v61, v61
	v_exp_f32_e32 v62, v62
	v_exp_f32_e32 v63, v63
	v_pk_add_f32 v[242:243], v[48:49], 0 op_sel_hi:[1,0]
	v_pk_add_f32 v[242:243], v[50:51], v[242:243]
	v_pk_add_f32 v[242:243], v[52:53], v[242:243]
	v_pk_add_f32 v[242:243], v[54:55], v[242:243]
	v_pk_add_f32 v[242:243], v[56:57], v[242:243]
	v_pk_add_f32 v[242:243], v[58:59], v[242:243]
	v_pk_add_f32 v[242:243], v[60:61], v[242:243]
	v_pk_add_f32 v[242:243], v[62:63], v[242:243]
	v_cvt_pk_bf16_f32 v48, v48, v49
	v_cvt_pk_bf16_f32 v49, v50, v51
	v_cvt_pk_bf16_f32 v50, v52, v53
	v_cvt_pk_bf16_f32 v51, v54, v55
	v_cvt_pk_bf16_f32 v52, v56, v57
	v_cvt_pk_bf16_f32 v53, v58, v59
	v_cvt_pk_bf16_f32 v54, v60, v61
	v_cvt_pk_bf16_f32 v55, v62, v63
	v_pk_mul_f32 v[16:17], v[16:17], v[238:239] op_sel_hi:[1,0]
	v_pk_mul_f32 v[18:19], v[18:19], v[238:239] op_sel_hi:[1,0]
	v_pk_mul_f32 v[20:21], v[20:21], v[238:239] op_sel_hi:[1,0]
	v_pk_mul_f32 v[22:23], v[22:23], v[238:239] op_sel_hi:[1,0]
	v_pk_mul_f32 v[24:25], v[24:25], v[238:239] op_sel_hi:[1,0]
	v_pk_mul_f32 v[26:27], v[26:27], v[238:239] op_sel_hi:[1,0]
	v_pk_mul_f32 v[28:29], v[28:29], v[238:239] op_sel_hi:[1,0]
	v_pk_mul_f32 v[30:31], v[30:31], v[238:239] op_sel_hi:[1,0]
	v_pk_mul_f32 v[0:1], v[0:1], v[238:239] op_sel_hi:[1,0]
	v_pk_mul_f32 v[2:3], v[2:3], v[238:239] op_sel_hi:[1,0]
	v_pk_mul_f32 v[4:5], v[4:5], v[238:239] op_sel_hi:[1,0]
	v_pk_mul_f32 v[6:7], v[6:7], v[238:239] op_sel_hi:[1,0]
	v_pk_mul_f32 v[8:9], v[8:9], v[238:239] op_sel_hi:[1,0]
	v_pk_mul_f32 v[10:11], v[10:11], v[238:239] op_sel_hi:[1,0]
	v_pk_mul_f32 v[12:13], v[12:13], v[238:239] op_sel_hi:[1,0]
	v_pk_mul_f32 v[14:15], v[14:15], v[238:239] op_sel_hi:[1,0]
	v_mfma_f32_32x32x16_bf16 v[16:31], v[202:205], v[48:51], v[16:31]
	ds_read_b128 v[202:205], v173
	v_pk_add_f32 v[32:33], v[32:33], v[236:237] op_sel_hi:[1,0] neg_lo:[0,1] neg_hi:[0,1]
	v_pk_add_f32 v[34:35], v[34:35], v[236:237] op_sel_hi:[1,0] neg_lo:[0,1] neg_hi:[0,1]
	v_pk_add_f32 v[36:37], v[36:37], v[236:237] op_sel_hi:[1,0] neg_lo:[0,1] neg_hi:[0,1]
	v_pk_add_f32 v[38:39], v[38:39], v[236:237] op_sel_hi:[1,0] neg_lo:[0,1] neg_hi:[0,1]
	v_pk_add_f32 v[40:41], v[40:41], v[236:237] op_sel_hi:[1,0] neg_lo:[0,1] neg_hi:[0,1]
	v_pk_add_f32 v[42:43], v[42:43], v[236:237] op_sel_hi:[1,0] neg_lo:[0,1] neg_hi:[0,1]
	v_pk_add_f32 v[44:45], v[44:45], v[236:237] op_sel_hi:[1,0] neg_lo:[0,1] neg_hi:[0,1]
	v_pk_add_f32 v[46:47], v[46:47], v[236:237] op_sel_hi:[1,0] neg_lo:[0,1] neg_hi:[0,1]
	v_exp_f32_e32 v32, v32
	v_exp_f32_e32 v33, v33
	v_mfma_f32_32x32x16_bf16 v[16:31], v[206:209], v[52:55], v[16:31]
	ds_read_b128 v[206:209], v173 offset:32
	v_exp_f32_e32 v34, v34
	v_exp_f32_e32 v35, v35
	v_exp_f32_e32 v36, v36
	v_exp_f32_e32 v37, v37
	v_exp_f32_e32 v38, v38
	v_exp_f32_e32 v39, v39
	v_exp_f32_e32 v40, v40
	v_exp_f32_e32 v41, v41
	v_exp_f32_e32 v42, v42
	v_exp_f32_e32 v43, v43
	v_mfma_f32_32x32x16_bf16 v[0:15], v[210:213], v[48:51], v[0:15]
	ds_read_b128 v[210:213], v173 offset:64
	v_exp_f32_e32 v44, v44
	v_exp_f32_e32 v45, v45
	v_exp_f32_e32 v46, v46
	v_exp_f32_e32 v47, v47
	v_pk_add_f32 v[242:243], v[32:33], v[242:243]
	v_pk_add_f32 v[242:243], v[34:35], v[242:243]
	v_pk_add_f32 v[242:243], v[36:37], v[242:243]
	v_pk_add_f32 v[242:243], v[38:39], v[242:243]
	v_pk_add_f32 v[242:243], v[40:41], v[242:243]
	v_pk_add_f32 v[242:243], v[42:43], v[242:243]
	v_mfma_f32_32x32x16_bf16 v[0:15], v[214:217], v[52:55], v[0:15]
	ds_read_b128 v[214:217], v173 offset:96
	v_pk_add_f32 v[242:243], v[44:45], v[242:243]
	v_pk_add_f32 v[242:243], v[46:47], v[242:243]
	v_cvt_pk_bf16_f32 v32, v32, v33
	v_cvt_pk_bf16_f32 v33, v34, v35
	v_cvt_pk_bf16_f32 v34, v36, v37
	v_cvt_pk_bf16_f32 v35, v38, v39
	v_cvt_pk_bf16_f32 v36, v40, v41
	v_cvt_pk_bf16_f32 v37, v42, v43
	v_cvt_pk_bf16_f32 v38, v44, v45
	v_cvt_pk_bf16_f32 v39, v46, v47
	v_add_f32_e32 v242, v242, v243
	v_fmac_f32_e32 v242, v182, v238
	v_mfma_f32_32x32x16_bf16 v[16:31], v[218:221], v[32:35], v[16:31]
	ds_read_b128 v[218:221], v173 offset:4608
	v_mfma_f32_32x32x16_bf16 v[16:31], v[222:225], v[36:39], v[16:31]
	ds_read_b128 v[222:225], v173 offset:4640
	v_mfma_f32_32x32x16_bf16 v[0:15], v[226:229], v[32:35], v[0:15]
	ds_read_b128 v[226:229], v173 offset:4672
	v_mfma_f32_32x32x16_bf16 v[0:15], v[230:233], v[36:39], v[0:15]
	ds_read_b128 v[230:233], v173 offset:4704
	v_mov_b32_e32 v182, v242
	v_mov_b32_e32 v183, v236
	v_add_u32_e32 v173, 0x2400, v173
	v_add_u32_e32 v234, 0x80, v234
	v_add_u32_e32 v235, 0x80, v235
	s_add_i32 s19, s19, 64
	v_subrev_u32_e32 v179, 64, v179
	v_add_u32_e32 v180, 64, v180
	s_add_i32 s21, s21, -1
	s_cmp_lg_u32 s21, 0
	s_cbranch_scc1 .Llat1_top
	v_mov_b32_e32 v54, v182
	v_mov_b32_e32 v156, v183
	s_branch .LBB0_387

.LBB0_389:
	s_andn2_b64 vcc, exec, s[4:5]
	s_cbranch_vccnz .LBB0_393
	s_movk_i32 s6, 0x90
	v_mad_u64_u32 v[32:33], s[4:5], v148, s6, v[146:147]
	s_barrier
	ds_write_b96 v32, v[112:114]
	ds_write_b32 v32, v149 offset:12
	ds_write_b16 v147, v163 offset:46080
	ds_write_b16_d16_hi v147, v163 offset:46728
	ds_write_b16 v147, v162 offset:47376
	ds_write_b16_d16_hi v147, v162 offset:48024
	ds_write_b16 v147, v161 offset:48672
	ds_write_b16_d16_hi v147, v161 offset:49320
	ds_write_b16 v147, v160 offset:49968
	ds_write_b16_d16_hi v147, v160 offset:50616
	v_mad_u64_u32 v[32:33], s[4:5], v150, s6, v[146:147]
	ds_write_b96 v32, v[116:118]
	ds_write_b32 v32, v164 offset:12
	ds_write_b16 v157, v168 offset:46080
	ds_write_b16_d16_hi v157, v168 offset:46728
	ds_write_b16 v157, v167 offset:47376
	ds_write_b16_d16_hi v157, v167 offset:48024
	ds_write_b16 v157, v166 offset:48672
	ds_write_b16_d16_hi v157, v166 offset:49320
	ds_write_b16 v157, v165 offset:49968
	ds_write_b16_d16_hi v157, v165 offset:50616
	v_mad_u64_u32 v[32:33], s[4:5], v152, s6, v[146:147]
	ds_write_b96 v32, v[120:122]
	ds_write_b32 v32, v153 offset:12
	ds_write_b16 v158, v172 offset:46080
	ds_write_b16_d16_hi v158, v172 offset:46728
	ds_write_b16 v158, v171 offset:47376
	ds_write_b16_d16_hi v158, v171 offset:48024
	ds_write_b16 v158, v170 offset:48672
	ds_write_b16_d16_hi v158, v170 offset:49320
	ds_write_b16 v158, v169 offset:49968
	ds_write_b16_d16_hi v158, v169 offset:50616
	v_mad_u64_u32 v[32:33], s[4:5], v154, s6, v[146:147]
	ds_write_b96 v32, v[124:126]
	ds_write_b32 v32, v174 offset:12
	ds_write_b16 v159, v178 offset:46080
	ds_write_b16_d16_hi v159, v178 offset:46728
	ds_write_b16 v159, v177 offset:47376
	ds_write_b16_d16_hi v159, v177 offset:48024
	ds_write_b16 v159, v176 offset:48672
	ds_write_b16_d16_hi v159, v176 offset:49320
	ds_write_b16 v159, v175 offset:49968
	ds_write_b16_d16_hi v159, v175 offset:50616
	v_and_b32_e32 v32, 64, v251
	v_xor_b32_e32 v155, 32, v251
	v_add_u32_e32 v173, 64, v32
	v_cmp_lt_i32_e32 vcc, v155, v173
	s_movk_i32 s2, 0x90
	s_mov_b32 s4, 0
	v_cndmask_b32_e32 v32, v251, v155, vcc
	v_lshlrev_b32_e32 v113, 2, v32
	s_waitcnt lgkmcnt(0)
	s_barrier
	v_mov_b32_e32 v244, v54
	s_mov_b32 s21, 4
	v_add_u32_e32 v234, 0xb400, v123
	v_add_u32_e32 v235, 0x10500, v123
	ds_read_b128 v[202:205], v127
	ds_read_b128 v[206:209], v127 offset:32
	ds_read_b128 v[210:213], v127 offset:64
	ds_read_b128 v[214:217], v127 offset:96
	ds_read_b128 v[218:221], v127 offset:4608
	ds_read_b128 v[222:225], v127 offset:4640
	ds_read_b128 v[226:229], v127 offset:4672
	ds_read_b128 v[230:233], v127 offset:4704
	v_add_u32_e32 v127, 0x2400, v127
.Llat2_top:
	s_waitcnt lgkmcnt(7)
	v_mfma_f32_32x32x16_bf16 v[48:63], v[202:205], v[96:99], 0
	ds_read2_b64 v[202:205], v234 offset1:2
	s_waitcnt lgkmcnt(7)
	v_mfma_f32_32x32x16_bf16 v[48:63], v[206:209], v[100:103], v[48:63]
	ds_read2_b64 v[206:209], v234 offset0:4 offset1:6
	s_waitcnt lgkmcnt(7)
	v_mfma_f32_32x32x16_bf16 v[48:63], v[210:213], v[104:107], v[48:63]
	ds_read2_b64 v[210:213], v235 offset1:2
	s_waitcnt lgkmcnt(7)
	v_mfma_f32_32x32x16_bf16 v[48:63], v[214:217], v[108:111], v[48:63]
	ds_read2_b64 v[214:217], v235 offset0:4 offset1:6
	s_waitcnt lgkmcnt(7)
	v_mfma_f32_32x32x16_bf16 v[32:47], v[218:221], v[96:99], 0
	ds_read2_b64 v[218:221], v234 offset0:8 offset1:10
	s_waitcnt lgkmcnt(7)
	v_mfma_f32_32x32x16_bf16 v[32:47], v[222:225], v[100:103], v[32:47]
	ds_read2_b64 v[222:225], v234 offset0:12 offset1:14
	s_waitcnt lgkmcnt(7)
	v_mfma_f32_32x32x16_bf16 v[32:47], v[226:229], v[104:107], v[32:47]
	ds_read2_b64 v[226:229], v235 offset0:8 offset1:10
	s_waitcnt lgkmcnt(7)
	v_mfma_f32_32x32x16_bf16 v[32:47], v[230:233], v[108:111], v[32:47]
	ds_read2_b64 v[230:233], v235 offset0:12 offset1:14
	v_max3_f32 v236, v48, s16, v49
	v_max3_f32 v236, v236, v50, v51
	v_max3_f32 v236, v236, v52, v53
	v_max3_f32 v236, v236, v54, v55
	v_max3_f32 v236, v236, v56, v57
	v_max3_f32 v236, v236, v58, v59
	v_max3_f32 v236, v236, v60, v61
	v_max3_f32 v236, v236, v62, v63
	s_nop 3
	v_max3_f32 v236, v236, v32, v33
	v_max3_f32 v236, v236, v34, v35
	v_max3_f32 v236, v236, v36, v37
	v_max3_f32 v236, v236, v38, v39
	v_max3_f32 v236, v236, v40, v41
	v_max3_f32 v236, v236, v42, v43
	v_max3_f32 v236, v236, v44, v45
	v_max3_f32 v236, v236, v46, v47
	ds_bpermute_b32 v237, v113, v236
	s_waitcnt lgkmcnt(0)
	v_max3_f32 v236, v156, v236, v237
	v_sub_f32_e32 v238, v156, v236
	v_pk_add_f32 v[48:49], v[48:49], v[236:237] op_sel_hi:[1,0] neg_lo:[0,1] neg_hi:[0,1]
	v_pk_add_f32 v[50:51], v[50:51], v[236:237] op_sel_hi:[1,0] neg_lo:[0,1] neg_hi:[0,1]
	v_pk_add_f32 v[52:53], v[52:53], v[236:237] op_sel_hi:[1,0] neg_lo:[0,1] neg_hi:[0,1]
	v_pk_add_f32 v[54:55], v[54:55], v[236:237] op_sel_hi:[1,0] neg_lo:[0,1] neg_hi:[0,1]
	v_pk_add_f32 v[56:57], v[56:57], v[236:237] op_sel_hi:[1,0] neg_lo:[0,1] neg_hi:[0,1]
	v_pk_add_f32 v[58:59], v[58:59], v[236:237] op_sel_hi:[1,0] neg_lo:[0,1] neg_hi:[0,1]
	v_pk_add_f32 v[60:61], v[60:61], v[236:237] op_sel_hi:[1,0] neg_lo:[0,1] neg_hi:[0,1]
	v_pk_add_f32 v[62:63], v[62:63], v[236:237] op_sel_hi:[1,0] neg_lo:[0,1] neg_hi:[0,1]
	v_exp_f32_e32 v238, v238
	v_exp_f32_e32 v48, v48
	v_exp_f32_e32 v49, v49
	v_exp_f32_e32 v50, v50
	v_exp_f32_e32 v51, v51
	v_exp_f32_e32 v52, v52
	v_exp_f32_e32 v53, v53
	v_exp_f32_e32 v54, v54
	v_exp_f32_e32 v55, v55
	v_exp_f32_e32 v56, v56
	v_exp_f32_e32 v57, v57
	v_exp_f32_e32 v58, v58
	v_exp_f32_e32 v59, v59
	v_exp_f32_e32 v60, v60
	v_exp_f32_e32 v61, v61
	v_exp_f32_e32 v62, v62
	v_exp_f32_e32 v63, v63
	v_pk_add_f32 v[242:243], v[48:49], 0 op_sel_hi:[1,0]
	v_pk_add_f32 v[242:243], v[50:51], v[242:243]
	v_pk_add_f32 v[242:243], v[52:53], v[242:243]
	v_pk_add_f32 v[242:243], v[54:55], v[242:243]
	v_pk_add_f32 v[242:243], v[56:57], v[242:243]
	v_pk_add_f32 v[242:243], v[58:59], v[242:243]
	v_pk_add_f32 v[242:243], v[60:61], v[242:243]
	v_pk_add_f32 v[242:243], v[62:63], v[242:243]
	v_cvt_pk_bf16_f32 v48, v48, v49
	v_cvt_pk_bf16_f32 v49, v50, v51
	v_cvt_pk_bf16_f32 v50, v52, v53
	v_cvt_pk_bf16_f32 v51, v54, v55
	v_cvt_pk_bf16_f32 v52, v56, v57
	v_cvt_pk_bf16_f32 v53, v58, v59
	v_cvt_pk_bf16_f32 v54, v60, v61
	v_cvt_pk_bf16_f32 v55, v62, v63
	v_pk_mul_f32 v[16:17], v[16:17], v[238:239] op_sel_hi:[1,0]
	v_pk_mul_f32 v[18:19], v[18:19], v[238:239] op_sel_hi:[1,0]
	v_pk_mul_f32 v[20:21], v[20:21], v[238:239] op_sel_hi:[1,0]
	v_pk_mul_f32 v[22:23], v[22:23], v[238:239] op_sel_hi:[1,0]
	v_pk_mul_f32 v[24:25], v[24:25], v[238:239] op_sel_hi:[1,0]
	v_pk_mul_f32 v[26:27], v[26:27], v[238:239] op_sel_hi:[1,0]
	v_pk_mul_f32 v[28:29], v[28:29], v[238:239] op_sel_hi:[1,0]
	v_pk_mul_f32 v[30:31], v[30:31], v[238:239] op_sel_hi:[1,0]
	v_pk_mul_f32 v[0:1], v[0:1], v[238:239] op_sel_hi:[1,0]
	v_pk_mul_f32 v[2:3], v[2:3], v[238:239] op_sel_hi:[1,0]
	v_pk_mul_f32 v[4:5], v[4:5], v[238:239] op_sel_hi:[1,0]
	v_pk_mul_f32 v[6:7], v[6:7], v[238:239] op_sel_hi:[1,0]
	v_pk_mul_f32 v[8:9], v[8:9], v[238:239] op_sel_hi:[1,0]
	v_pk_mul_f32 v[10:11], v[10:11], v[238:239] op_sel_hi:[1,0]
	v_pk_mul_f32 v[12:13], v[12:13], v[238:239] op_sel_hi:[1,0]
	v_pk_mul_f32 v[14:15], v[14:15], v[238:239] op_sel_hi:[1,0]
	v_mfma_f32_32x32x16_bf16 v[16:31], v[202:205], v[48:51], v[16:31]
	ds_read_b128 v[202:205], v127
	v_pk_add_f32 v[32:33], v[32:33], v[236:237] op_sel_hi:[1,0] neg_lo:[0,1] neg_hi:[0,1]
	v_pk_add_f32 v[34:35], v[34:35], v[236:237] op_sel_hi:[1,0] neg_lo:[0,1] neg_hi:[0,1]
	v_pk_add_f32 v[36:37], v[36:37], v[236:237] op_sel_hi:[1,0] neg_lo:[0,1] neg_hi:[0,1]
	v_pk_add_f32 v[38:39], v[38:39], v[236:237] op_sel_hi:[1,0] neg_lo:[0,1] neg_hi:[0,1]
	v_pk_add_f32 v[40:41], v[40:41], v[236:237] op_sel_hi:[1,0] neg_lo:[0,1] neg_hi:[0,1]
	v_pk_add_f32 v[42:43], v[42:43], v[236:237] op_sel_hi:[1,0] neg_lo:[0,1] neg_hi:[0,1]
	v_pk_add_f32 v[44:45], v[44:45], v[236:237] op_sel_hi:[1,0] neg_lo:[0,1] neg_hi:[0,1]
	v_pk_add_f32 v[46:47], v[46:47], v[236:237] op_sel_hi:[1,0] neg_lo:[0,1] neg_hi:[0,1]
	v_exp_f32_e32 v32, v32
	v_exp_f32_e32 v33, v33
	v_mfma_f32_32x32x16_bf16 v[16:31], v[206:209], v[52:55], v[16:31]
	ds_read_b128 v[206:209], v127 offset:32
	v_exp_f32_e32 v34, v34
	v_exp_f32_e32 v35, v35
	v_exp_f32_e32 v36, v36
	v_exp_f32_e32 v37, v37
	v_exp_f32_e32 v38, v38
	v_exp_f32_e32 v39, v39
	v_exp_f32_e32 v40, v40
	v_exp_f32_e32 v41, v41
	v_exp_f32_e32 v42, v42
	v_exp_f32_e32 v43, v43
	v_mfma_f32_32x32x16_bf16 v[0:15], v[210:213], v[48:51], v[0:15]
	ds_read_b128 v[210:213], v127 offset:64
	v_exp_f32_e32 v44, v44
	v_exp_f32_e32 v45, v45
	v_exp_f32_e32 v46, v46
	v_exp_f32_e32 v47, v47
	v_pk_add_f32 v[242:243], v[32:33], v[242:243]
	v_pk_add_f32 v[242:243], v[34:35], v[242:243]
	v_pk_add_f32 v[242:243], v[36:37], v[242:243]
	v_pk_add_f32 v[242:243], v[38:39], v[242:243]
	v_pk_add_f32 v[242:243], v[40:41], v[242:243]
	v_pk_add_f32 v[242:243], v[42:43], v[242:243]
	v_mfma_f32_32x32x16_bf16 v[0:15], v[214:217], v[52:55], v[0:15]
	ds_read_b128 v[214:217], v127 offset:96
	v_pk_add_f32 v[242:243], v[44:45], v[242:243]
	v_pk_add_f32 v[242:243], v[46:47], v[242:243]
	v_cvt_pk_bf16_f32 v32, v32, v33
	v_cvt_pk_bf16_f32 v33, v34, v35
	v_cvt_pk_bf16_f32 v34, v36, v37
	v_cvt_pk_bf16_f32 v35, v38, v39
	v_cvt_pk_bf16_f32 v36, v40, v41
	v_cvt_pk_bf16_f32 v37, v42, v43
	v_cvt_pk_bf16_f32 v38, v44, v45
	v_cvt_pk_bf16_f32 v39, v46, v47
	v_add_f32_e32 v242, v242, v243
	v_fmac_f32_e32 v242, v244, v238
	v_mfma_f32_32x32x16_bf16 v[16:31], v[218:221], v[32:35], v[16:31]
	ds_read_b128 v[218:221], v127 offset:4608
	v_mfma_f32_32x32x16_bf16 v[16:31], v[222:225], v[36:39], v[16:31]
	ds_read_b128 v[222:225], v127 offset:4640
	v_mfma_f32_32x32x16_bf16 v[0:15], v[226:229], v[32:35], v[0:15]
	ds_read_b128 v[226:229], v127 offset:4672
	v_mfma_f32_32x32x16_bf16 v[0:15], v[230:233], v[36:39], v[0:15]
	ds_read_b128 v[230:233], v127 offset:4704
	v_mov_b32_e32 v244, v242
	v_mov_b32_e32 v156, v236
	v_add_u32_e32 v127, 0x2400, v127
	v_add_u32_e32 v234, 0x80, v234
	v_add_u32_e32 v235, 0x80, v235
	s_add_i32 s21, s21, -1
	s_cmp_lg_u32 s21, 0
	s_cbranch_scc1 .Llat2_top
	v_mov_b32_e32 v54, v244
	v_mov_b32_e32 v32, v251
